# adds: phase-0 prep_rows x rows prefetched at phase entry (static 8 rows/wave) + grid-barrier leader no longer waits for its release atomics
# baseline (speedup 1.0000x reference)
; __device__ __forceinline__ unsigned xb_add(unsigned* p, unsigned v) { return __hip_atomic_fetch_add(p, v, __ATOMIC_RELAXED, __HIP_MEMORY_SCOPE_AGENT); }
; __device__ __forceinline__ void xcd_barrier(const XcdBarrier& b) {
;     ...
;             __builtin_amdgcn_fence(__ATOMIC_ACQUIRE, "agent");
;             xb_add(&bar[XB_XGEN(b.x)], 1u);
;             asm volatile("s_waitcnt vmcnt(0)" ::: "memory");
;         } else {
.LBB0_71:
	s_or_b64 exec, exec, s[10:11]
	s_mov_b64 s[10:11], exec
	v_mbcnt_lo_u32_b32 v0, s10, 0
	v_mbcnt_hi_u32_b32 v0, s11, v0
	v_cmp_eq_u32_e32 vcc, 0, v0
	s_and_saveexec_b64 s[16:17], vcc
	s_cbranch_execz .LBB0_73
	s_bcnt1_i32_b64 s3, s[10:11]
	v_readlane_b32 s10, v252, 10
	v_mov_b32_e32 v0, s3
	v_readlane_b32 s11, v252, 11
	s_nop 4
	global_atomic_add v1, v0, s[10:11]
.LBB0_73:
	s_or_b64 exec, exec, s[16:17]
.LBB0_74:
	s_or_b64 exec, exec, s[0:1]
	s_waitcnt lgkmcnt(0)
	s_barrier

; __device__ __forceinline__ int tid_opq() { int t = threadIdx.x; asm volatile("" : "+v"(t)); return t; }
; __device__ __forceinline__ int bid_opq() { int b = blockIdx.x; asm volatile("" : "+s"(b)); return b; }
;     ...
;     const int tid = tid_opq(), ntn = N / 128, nt = (K / 64) * ntn;
;     const int lk = tid >> 5, ln4 = (tid & 31) * 4;
;     f32x4 v[4];
;     const int tstride = nblk ? nblk : (int)gridDim.x;
;     int t = bid_opq() - first;
;     if (t < nt) { const int k0 = (t / ntn) * 64, n0 = (t % ntn) * 128;
; #pragma unroll
;         for (int i = 0; i < 4; ++i) v[i] = *(const f32x4*)(W + (size_t)(k0 + lk + 16 * i) * N + n0 + ln4); }
; __device__ void prep_rows(const float* __restrict__ X, bf16_t* __restrict__ XB, float* __restrict__ PS, int rows) {
;     ...
;     for (int r = gw; r < rows; r += stride) {
;         const f32x4* xr = (const f32x4*)(X + (size_t)r * DM); float ss = 0.f;
; #pragma unroll
;         for (int i = 0; i < 4; ++i) { const f32x4 v = xr[lane + 64 * i]; ss += v[0] * v[0] + v[1] * v[1] + v[2] * v[2] + v[3] * v[3];
.LBB0_598:
	v_readlane_b32 s0, v249, 11
	v_readlane_b32 s1, v249, 12
	v_lshrrev_b32_e32 v216, 6, v187
	v_lshl_add_u32 v216, s2, 3, v216
	v_mov_b32_e32 v217, 0
	v_and_b32_e32 v218, 63, v187
	v_lshlrev_b64 v[216:217], 12, v[216:217]
	v_lshl_or_b32 v216, v218, 4, v216
	v_lshl_add_u64 v[216:217], s[0:1], 0, v[216:217]
	s_mov_b64 s[0:1], 0x800000
	global_load_dwordx4 v[60:63], v[216:217], off offset:-3072
	global_load_dwordx4 v[64:67], v[216:217], off offset:-2048
	global_load_dwordx4 v[68:71], v[216:217], off offset:-1024
	global_load_dwordx4 v[72:75], v[216:217], off
	v_lshl_add_u64 v[216:217], v[216:217], 0, s[0:1]
	global_load_dwordx4 v[76:79], v[216:217], off offset:-3072
	global_load_dwordx4 v[80:83], v[216:217], off offset:-2048
	global_load_dwordx4 v[84:87], v[216:217], off offset:-1024
	global_load_dwordx4 v[88:91], v[216:217], off
	v_lshl_add_u64 v[216:217], v[216:217], 0, s[0:1]
	global_load_dwordx4 v[92:95], v[216:217], off offset:-3072
	global_load_dwordx4 v[96:99], v[216:217], off offset:-2048
	global_load_dwordx4 v[100:103], v[216:217], off offset:-1024
	global_load_dwordx4 v[104:107], v[216:217], off
	v_lshl_add_u64 v[216:217], v[216:217], 0, s[0:1]
	global_load_dwordx4 v[108:111], v[216:217], off offset:-3072
	global_load_dwordx4 v[112:115], v[216:217], off offset:-2048
	global_load_dwordx4 v[116:119], v[216:217], off offset:-1024
	global_load_dwordx4 v[120:123], v[216:217], off
	v_lshl_add_u64 v[216:217], v[216:217], 0, s[0:1]
	global_load_dwordx4 v[124:127], v[216:217], off offset:-3072
	global_load_dwordx4 v[128:131], v[216:217], off offset:-2048
	global_load_dwordx4 v[132:135], v[216:217], off offset:-1024
	global_load_dwordx4 v[136:139], v[216:217], off
	v_lshl_add_u64 v[216:217], v[216:217], 0, s[0:1]
	global_load_dwordx4 v[140:143], v[216:217], off offset:-3072
	global_load_dwordx4 v[144:147], v[216:217], off offset:-2048
	global_load_dwordx4 v[148:151], v[216:217], off offset:-1024
	global_load_dwordx4 v[152:155], v[216:217], off
	v_lshl_add_u64 v[216:217], v[216:217], 0, s[0:1]
	global_load_dwordx4 v[156:159], v[216:217], off offset:-3072
	global_load_dwordx4 v[160:163], v[216:217], off offset:-2048
	global_load_dwordx4 v[164:167], v[216:217], off offset:-1024
	global_load_dwordx4 v[168:171], v[216:217], off
	v_lshl_add_u64 v[216:217], v[216:217], 0, s[0:1]
	global_load_dwordx4 v[200:203], v[216:217], off offset:-3072
	global_load_dwordx4 v[204:207], v[216:217], off offset:-2048
	global_load_dwordx4 v[208:211], v[216:217], off offset:-1024
	global_load_dwordx4 v[212:215], v[216:217], off
	v_mov_b32_e32 v18, v187
	s_mov_b32 s3, s2
	s_cmpk_gt_i32 s3, 0x15f
	s_cbranch_scc1 .LBB0_611
	s_mul_hi_i32 s0, s3, 0x2e8ba2e9
	s_lshr_b32 s1, s0, 31
	s_ashr_i32 s0, s0, 2
	s_add_i32 s1, s0, s1
	s_mul_i32 s0, s1, 22
	s_sub_i32 s0, s3, s0
	v_ashrrev_i32_e32 v22, 5, v18
	s_lshl_b32 s0, s0, 7
	s_waitcnt vmcnt(0)
	v_lshl_add_u32 v14, s1, 6, v22
	s_ashr_i32 s1, s0, 31
	v_readlane_b32 s68, v250, 59
	s_lshl_b64 s[0:1], s[0:1], 2
	v_readlane_b32 s74, v249, 1
	v_readlane_b32 s75, v249, 2
	s_add_u32 s0, s74, s0
	v_lshlrev_b32_e32 v0, 4, v18
	s_addc_u32 s1, s75, s1
	v_and_b32_e32 v0, 0x1f0, v0
	v_lshl_add_u64 v[10:11], s[0:1], 0, v[0:1]
	s_movk_i32 s10, 0x2c00
	s_waitcnt lgkmcnt(1)
	v_mad_i64_i32 v[2:3], s[0:1], v14, s10, v[10:11]
	s_waitcnt lgkmcnt(0)
	v_add_u32_e32 v4, 16, v14
	v_add_u32_e32 v12, 32, v14
	v_add_u32_e32 v14, 48, v14
	v_mad_i64_i32 v[6:7], s[0:1], v4, s10, v[10:11]
	v_mad_i64_i32 v[12:13], s[0:1], v12, s10, v[10:11]
	v_mad_i64_i32 v[14:15], s[0:1], v14, s10, v[10:11]
	global_load_dwordx4 v[2:5], v[2:3], off
	s_nop 0
	global_load_dwordx4 v[6:9], v[6:7], off
	s_nop 0
	global_load_dwordx4 v[10:13], v[12:13], off
	s_nop 0
	global_load_dwordx4 v[14:17], v[14:15], off
	v_add_u32_e32 v19, 0, v0
	v_lshl_add_u64 v[24:25], s[74:75], 0, v[0:1]
	v_lshlrev_b32_e32 v0, 3, v18
	v_ashrrev_i32_e32 v20, 3, v18
	v_and_b32_e32 v18, 56, v0
	v_lshlrev_b32_e32 v0, 1, v18
	s_movk_i32 s0, 0x204
	v_lshl_add_u64 v[26:27], s[24:25], 0, v[0:1]
	v_add_u32_e32 v21, 64, v20
	v_lshl_add_u32 v28, v20, 2, 0
	v_mul_u32_u24_e32 v18, 0x204, v18
	v_mul_lo_u32 v29, v22, s0
	v_and_b32_e32 v0, 0x7f, v20
	v_lshlrev_b32_e32 v20, 1, v20
	s_add_i32 s0, s34, s3
	v_and_b32_e32 v32, 0x7f, v21
	v_ashrrev_i32_e32 v23, 31, v22
	v_lshl_add_u32 v33, s3, 8, v20
	s_lshl_b32 s14, s34, 8
	s_lshl_b32 s15, s0, 7
	s_lshl_b32 s18, s34, 7
	v_add_u32_e32 v34, v28, v18
	v_add_u32_e32 v35, v19, v29
	v_readlane_b32 s69, v250, 60
	v_readlane_b32 s70, v250, 61
	v_readlane_b32 s71, v250, 62
	v_readlane_b32 s72, v250, 63
	v_readlane_b32 s73, v249, 0
	v_readlane_b32 s76, v249, 3
	v_readlane_b32 s77, v249, 4
	v_readlane_b32 s78, v249, 5
	v_readlane_b32 s79, v249, 6
	v_readlane_b32 s80, v249, 7
	v_readlane_b32 s81, v249, 8
	v_readlane_b32 s82, v249, 9
	v_readlane_b32 s83, v249, 10
	s_branch .LBB0_601

; __device__ __forceinline__ unsigned cvtpk(float lo, float hi) { f32x2_t v = {lo, hi}; bf16x2_t b = __builtin_convertvector(v, bf16x2_t); return __builtin_bit_cast(unsigned, b); }
; __device__ __forceinline__ float wave_sum(float v) { v += __shfl_xor(v, 32); v += __shfl_xor(v, 16); v += __shfl_xor(v, 8); v += __shfl_xor(v, 4); v += __shfl_xor(v, 2); v += __shfl_xor(v, 1); return v; }
; __device__ void prep_rows(const float* __restrict__ X, bf16_t* __restrict__ XB, float* __restrict__ PS, int rows) {
;     ...
;     for (int r = gw; r < rows; r += stride) {
;         const f32x4* xr = (const f32x4*)(X + (size_t)r * DM); float ss = 0.f;
; #pragma unroll
;         for (int i = 0; i < 4; ++i) { const f32x4 v = xr[lane + 64 * i]; ss += v[0] * v[0] + v[1] * v[1] + v[2] * v[2] + v[3] * v[3];
;             u32x2 w; w.x = cvtpk(v[0], v[1]); w.y = cvtpk(v[2], v[3]); *(u32x2*)(XB + (size_t)r * DM + (lane + 64 * i) * 4) = w; }
;         ss = wave_sum(ss);
;         if (lane == 0) PS[r] = ss;
;     }
.LBB0_661:
	s_waitcnt vmcnt(0) lgkmcnt(0)
	v_mul_f32_e32 v30, v61, v61
	v_mul_f32_e32 v31, v65, v65
	v_mul_f32_e32 v32, v69, v69
	v_fmac_f32_e32 v30, v60, v60
	v_fmac_f32_e32 v31, v64, v64
	v_mul_f32_e32 v33, v73, v73
	v_fmac_f32_e32 v32, v68, v68
	v_fmac_f32_e32 v30, v62, v62
	v_fmac_f32_e32 v31, v66, v66
	v_fmac_f32_e32 v33, v72, v72
	v_fmac_f32_e32 v32, v70, v70
	v_fmac_f32_e32 v30, v63, v63
	v_fmac_f32_e32 v31, v67, v67
	v_fmac_f32_e32 v33, v74, v74
	v_fmac_f32_e32 v32, v71, v71
	v_add_f32_e32 v30, v30, v31
	v_add_f32_e32 v30, v30, v32
	v_fmac_f32_e32 v33, v75, v75
	v_add_f32_e32 v30, v30, v33
	ds_bpermute_b32 v31, v8, v30
	v_cvt_pk_bf16_f32 v14, v60, v61
	v_cvt_pk_bf16_f32 v15, v62, v63
	global_store_dwordx2 v[4:5], v[14:15], off offset:-1024
	v_cvt_pk_bf16_f32 v16, v64, v65
	s_waitcnt lgkmcnt(0)
	v_add_f32_e32 v30, v30, v31
	ds_bpermute_b32 v31, v9, v30
	v_cvt_pk_bf16_f32 v17, v66, v67
	global_store_dwordx2 v[4:5], v[16:17], off offset:-512
	v_cvt_pk_bf16_f32 v18, v68, v69
	v_cvt_pk_bf16_f32 v19, v70, v71
	s_waitcnt lgkmcnt(0)
	v_add_f32_e32 v30, v30, v31
	ds_bpermute_b32 v31, v10, v30
	global_store_dwordx2 v[4:5], v[18:19], off
	v_cvt_pk_bf16_f32 v20, v72, v73
	v_cvt_pk_bf16_f32 v21, v74, v75
	global_store_dwordx2 v[4:5], v[20:21], off offset:512
	s_waitcnt lgkmcnt(0)
	v_add_f32_e32 v30, v30, v31
	ds_bpermute_b32 v31, v11, v30
	s_waitcnt lgkmcnt(0)
	v_add_f32_e32 v22, v30, v31
	ds_bpermute_b32 v23, v12, v22
	s_waitcnt lgkmcnt(0)
	v_add_f32_e32 v24, v22, v23
	ds_bpermute_b32 v25, v13, v24
	s_and_saveexec_b64 s[0:1], vcc
	s_cbranch_execz .Lprep_skip0
	s_waitcnt lgkmcnt(0)
	v_add_f32_e32 v24, v24, v25
	global_store_dword v[2:3], v24, off
.Lprep_skip0:
	s_or_b64 exec, exec, s[0:1]
	v_lshl_add_u64 v[2:3], v[2:3], 0, s[50:51]
	v_lshl_add_u64 v[4:5], v[4:5], 0, s[52:53]
	v_mul_f32_e32 v30, v77, v77
	v_mul_f32_e32 v31, v81, v81
	v_mul_f32_e32 v32, v85, v85
	v_fmac_f32_e32 v30, v76, v76
	v_fmac_f32_e32 v31, v80, v80
	v_mul_f32_e32 v33, v89, v89
	v_fmac_f32_e32 v32, v84, v84
	v_fmac_f32_e32 v30, v78, v78
	v_fmac_f32_e32 v31, v82, v82
	v_fmac_f32_e32 v33, v88, v88
	v_fmac_f32_e32 v32, v86, v86
	v_fmac_f32_e32 v30, v79, v79
	v_fmac_f32_e32 v31, v83, v83
	v_fmac_f32_e32 v33, v90, v90
	v_fmac_f32_e32 v32, v87, v87
	v_add_f32_e32 v30, v30, v31
	v_add_f32_e32 v30, v30, v32
	v_fmac_f32_e32 v33, v91, v91
	v_add_f32_e32 v30, v30, v33
	ds_bpermute_b32 v31, v8, v30
	v_cvt_pk_bf16_f32 v14, v76, v77
	v_cvt_pk_bf16_f32 v15, v78, v79
	global_store_dwordx2 v[4:5], v[14:15], off offset:-1024
	v_cvt_pk_bf16_f32 v16, v80, v81
	s_waitcnt lgkmcnt(0)
	v_add_f32_e32 v30, v30, v31
	ds_bpermute_b32 v31, v9, v30
	v_cvt_pk_bf16_f32 v17, v82, v83
	global_store_dwordx2 v[4:5], v[16:17], off offset:-512
	v_cvt_pk_bf16_f32 v18, v84, v85
	v_cvt_pk_bf16_f32 v19, v86, v87
	s_waitcnt lgkmcnt(0)
	v_add_f32_e32 v30, v30, v31
	ds_bpermute_b32 v31, v10, v30
	global_store_dwordx2 v[4:5], v[18:19], off
	v_cvt_pk_bf16_f32 v20, v88, v89
	v_cvt_pk_bf16_f32 v21, v90, v91
	global_store_dwordx2 v[4:5], v[20:21], off offset:512
	s_waitcnt lgkmcnt(0)
	v_add_f32_e32 v30, v30, v31
	ds_bpermute_b32 v31, v11, v30
	s_waitcnt lgkmcnt(0)
	v_add_f32_e32 v22, v30, v31
	ds_bpermute_b32 v23, v12, v22
	s_waitcnt lgkmcnt(0)
	v_add_f32_e32 v24, v22, v23
	ds_bpermute_b32 v25, v13, v24
	s_and_saveexec_b64 s[0:1], vcc
	s_cbranch_execz .Lprep_skip1
	s_waitcnt lgkmcnt(0)
	v_add_f32_e32 v24, v24, v25
	global_store_dword v[2:3], v24, off
.Lprep_skip1:
	s_or_b64 exec, exec, s[0:1]
	v_lshl_add_u64 v[2:3], v[2:3], 0, s[50:51]
	v_lshl_add_u64 v[4:5], v[4:5], 0, s[52:53]
	v_mul_f32_e32 v30, v93, v93
	v_mul_f32_e32 v31, v97, v97
	v_mul_f32_e32 v32, v101, v101
	v_fmac_f32_e32 v30, v92, v92
	v_fmac_f32_e32 v31, v96, v96
	v_mul_f32_e32 v33, v105, v105
	v_fmac_f32_e32 v32, v100, v100
	v_fmac_f32_e32 v30, v94, v94
	v_fmac_f32_e32 v31, v98, v98
	v_fmac_f32_e32 v33, v104, v104
	v_fmac_f32_e32 v32, v102, v102
	v_fmac_f32_e32 v30, v95, v95
	v_fmac_f32_e32 v31, v99, v99
	v_fmac_f32_e32 v33, v106, v106
	v_fmac_f32_e32 v32, v103, v103
	v_add_f32_e32 v30, v30, v31
	v_add_f32_e32 v30, v30, v32
	v_fmac_f32_e32 v33, v107, v107
	v_add_f32_e32 v30, v30, v33
	ds_bpermute_b32 v31, v8, v30
	v_cvt_pk_bf16_f32 v14, v92, v93
	v_cvt_pk_bf16_f32 v15, v94, v95
	global_store_dwordx2 v[4:5], v[14:15], off offset:-1024
	v_cvt_pk_bf16_f32 v16, v96, v97
	s_waitcnt lgkmcnt(0)
	v_add_f32_e32 v30, v30, v31
	ds_bpermute_b32 v31, v9, v30
	v_cvt_pk_bf16_f32 v17, v98, v99
	global_store_dwordx2 v[4:5], v[16:17], off offset:-512
	v_cvt_pk_bf16_f32 v18, v100, v101
	v_cvt_pk_bf16_f32 v19, v102, v103
	s_waitcnt lgkmcnt(0)
	v_add_f32_e32 v30, v30, v31
	ds_bpermute_b32 v31, v10, v30
	global_store_dwordx2 v[4:5], v[18:19], off
	v_cvt_pk_bf16_f32 v20, v104, v105
	v_cvt_pk_bf16_f32 v21, v106, v107
	global_store_dwordx2 v[4:5], v[20:21], off offset:512
	s_waitcnt lgkmcnt(0)
	v_add_f32_e32 v30, v30, v31
	ds_bpermute_b32 v31, v11, v30
	s_waitcnt lgkmcnt(0)
	v_add_f32_e32 v22, v30, v31
	ds_bpermute_b32 v23, v12, v22
	s_waitcnt lgkmcnt(0)
	v_add_f32_e32 v24, v22, v23
	ds_bpermute_b32 v25, v13, v24
	s_and_saveexec_b64 s[0:1], vcc
	s_cbranch_execz .Lprep_skip2
	s_waitcnt lgkmcnt(0)
	v_add_f32_e32 v24, v24, v25
	global_store_dword v[2:3], v24, off
; __device__ __forceinline__ unsigned cvtpk(float lo, float hi) { f32x2_t v = {lo, hi}; bf16x2_t b = __builtin_convertvector(v, bf16x2_t); return __builtin_bit_cast(unsigned, b); }
; __device__ __forceinline__ float wave_sum(float v) { v += __shfl_xor(v, 32); v += __shfl_xor(v, 16); v += __shfl_xor(v, 8); v += __shfl_xor(v, 4); v += __shfl_xor(v, 2); v += __shfl_xor(v, 1); return v; }
; __device__ void prep_rows(const float* __restrict__ X, bf16_t* __restrict__ XB, float* __restrict__ PS, int rows) {
;     ...
;     for (int r = gw; r < rows; r += stride) {
;         const f32x4* xr = (const f32x4*)(X + (size_t)r * DM); float ss = 0.f;
; #pragma unroll
;         for (int i = 0; i < 4; ++i) { const f32x4 v = xr[lane + 64 * i]; ss += v[0] * v[0] + v[1] * v[1] + v[2] * v[2] + v[3] * v[3];
;             u32x2 w; w.x = cvtpk(v[0], v[1]); w.y = cvtpk(v[2], v[3]); *(u32x2*)(XB + (size_t)r * DM + (lane + 64 * i) * 4) = w; }
;         ss = wave_sum(ss);
;         if (lane == 0) PS[r] = ss;
;     }
.Lprep_skip2:
	s_or_b64 exec, exec, s[0:1]
	v_lshl_add_u64 v[2:3], v[2:3], 0, s[50:51]
	v_lshl_add_u64 v[4:5], v[4:5], 0, s[52:53]
	v_mul_f32_e32 v30, v109, v109
	v_mul_f32_e32 v31, v113, v113
	v_mul_f32_e32 v32, v117, v117
	v_fmac_f32_e32 v30, v108, v108
	v_fmac_f32_e32 v31, v112, v112
	v_mul_f32_e32 v33, v121, v121
	v_fmac_f32_e32 v32, v116, v116
	v_fmac_f32_e32 v30, v110, v110
	v_fmac_f32_e32 v31, v114, v114
	v_fmac_f32_e32 v33, v120, v120
	v_fmac_f32_e32 v32, v118, v118
	v_fmac_f32_e32 v30, v111, v111
	v_fmac_f32_e32 v31, v115, v115
	v_fmac_f32_e32 v33, v122, v122
	v_fmac_f32_e32 v32, v119, v119
	v_add_f32_e32 v30, v30, v31
	v_add_f32_e32 v30, v30, v32
	v_fmac_f32_e32 v33, v123, v123
	v_add_f32_e32 v30, v30, v33
	ds_bpermute_b32 v31, v8, v30
	v_cvt_pk_bf16_f32 v14, v108, v109
	v_cvt_pk_bf16_f32 v15, v110, v111
	global_store_dwordx2 v[4:5], v[14:15], off offset:-1024
	v_cvt_pk_bf16_f32 v16, v112, v113
	s_waitcnt lgkmcnt(0)
	v_add_f32_e32 v30, v30, v31
	ds_bpermute_b32 v31, v9, v30
	v_cvt_pk_bf16_f32 v17, v114, v115
	global_store_dwordx2 v[4:5], v[16:17], off offset:-512
	v_cvt_pk_bf16_f32 v18, v116, v117
	v_cvt_pk_bf16_f32 v19, v118, v119
	s_waitcnt lgkmcnt(0)
	v_add_f32_e32 v30, v30, v31
	ds_bpermute_b32 v31, v10, v30
	global_store_dwordx2 v[4:5], v[18:19], off
	v_cvt_pk_bf16_f32 v20, v120, v121
	v_cvt_pk_bf16_f32 v21, v122, v123
	global_store_dwordx2 v[4:5], v[20:21], off offset:512
	s_waitcnt lgkmcnt(0)
	v_add_f32_e32 v30, v30, v31
	ds_bpermute_b32 v31, v11, v30
	s_waitcnt lgkmcnt(0)
	v_add_f32_e32 v22, v30, v31
	ds_bpermute_b32 v23, v12, v22
	s_waitcnt lgkmcnt(0)
	v_add_f32_e32 v24, v22, v23
	ds_bpermute_b32 v25, v13, v24
	s_and_saveexec_b64 s[0:1], vcc
	s_cbranch_execz .Lprep_skip3
	s_waitcnt lgkmcnt(0)
	v_add_f32_e32 v24, v24, v25
	global_store_dword v[2:3], v24, off
.Lprep_skip3:
	s_or_b64 exec, exec, s[0:1]
	v_lshl_add_u64 v[2:3], v[2:3], 0, s[50:51]
	v_lshl_add_u64 v[4:5], v[4:5], 0, s[52:53]
	v_mul_f32_e32 v30, v125, v125
	v_mul_f32_e32 v31, v129, v129
	v_mul_f32_e32 v32, v133, v133
	v_fmac_f32_e32 v30, v124, v124
	v_fmac_f32_e32 v31, v128, v128
	v_mul_f32_e32 v33, v137, v137
	v_fmac_f32_e32 v32, v132, v132
	v_fmac_f32_e32 v30, v126, v126
	v_fmac_f32_e32 v31, v130, v130
	v_fmac_f32_e32 v33, v136, v136
	v_fmac_f32_e32 v32, v134, v134
	v_fmac_f32_e32 v30, v127, v127
	v_fmac_f32_e32 v31, v131, v131
	v_fmac_f32_e32 v33, v138, v138
	v_fmac_f32_e32 v32, v135, v135
	v_add_f32_e32 v30, v30, v31
	v_add_f32_e32 v30, v30, v32
	v_fmac_f32_e32 v33, v139, v139
	v_add_f32_e32 v30, v30, v33
	ds_bpermute_b32 v31, v8, v30
	v_cvt_pk_bf16_f32 v14, v124, v125
	v_cvt_pk_bf16_f32 v15, v126, v127
	global_store_dwordx2 v[4:5], v[14:15], off offset:-1024
	v_cvt_pk_bf16_f32 v16, v128, v129
	s_waitcnt lgkmcnt(0)
	v_add_f32_e32 v30, v30, v31
	ds_bpermute_b32 v31, v9, v30
	v_cvt_pk_bf16_f32 v17, v130, v131
	global_store_dwordx2 v[4:5], v[16:17], off offset:-512
	v_cvt_pk_bf16_f32 v18, v132, v133
	v_cvt_pk_bf16_f32 v19, v134, v135
	s_waitcnt lgkmcnt(0)
	v_add_f32_e32 v30, v30, v31
	ds_bpermute_b32 v31, v10, v30
	global_store_dwordx2 v[4:5], v[18:19], off
	v_cvt_pk_bf16_f32 v20, v136, v137
	v_cvt_pk_bf16_f32 v21, v138, v139
	global_store_dwordx2 v[4:5], v[20:21], off offset:512
	s_waitcnt lgkmcnt(0)
	v_add_f32_e32 v30, v30, v31
	ds_bpermute_b32 v31, v11, v30
	s_waitcnt lgkmcnt(0)
	v_add_f32_e32 v22, v30, v31
	ds_bpermute_b32 v23, v12, v22
	s_waitcnt lgkmcnt(0)
	v_add_f32_e32 v24, v22, v23
	ds_bpermute_b32 v25, v13, v24
	s_and_saveexec_b64 s[0:1], vcc
	s_cbranch_execz .Lprep_skip4
	s_waitcnt lgkmcnt(0)
	v_add_f32_e32 v24, v24, v25
	global_store_dword v[2:3], v24, off
.Lprep_skip4:
	s_or_b64 exec, exec, s[0:1]
	v_lshl_add_u64 v[2:3], v[2:3], 0, s[50:51]
	v_lshl_add_u64 v[4:5], v[4:5], 0, s[52:53]
	v_mul_f32_e32 v30, v141, v141
	v_mul_f32_e32 v31, v145, v145
	v_mul_f32_e32 v32, v149, v149
	v_fmac_f32_e32 v30, v140, v140
	v_fmac_f32_e32 v31, v144, v144
	v_mul_f32_e32 v33, v153, v153
	v_fmac_f32_e32 v32, v148, v148
	v_fmac_f32_e32 v30, v142, v142
	v_fmac_f32_e32 v31, v146, v146
	v_fmac_f32_e32 v33, v152, v152
	v_fmac_f32_e32 v32, v150, v150
	v_fmac_f32_e32 v30, v143, v143
	v_fmac_f32_e32 v31, v147, v147
	v_fmac_f32_e32 v33, v154, v154
	v_fmac_f32_e32 v32, v151, v151
	v_add_f32_e32 v30, v30, v31
	v_add_f32_e32 v30, v30, v32
	v_fmac_f32_e32 v33, v155, v155
	v_add_f32_e32 v30, v30, v33
	ds_bpermute_b32 v31, v8, v30
	v_cvt_pk_bf16_f32 v14, v140, v141
	v_cvt_pk_bf16_f32 v15, v142, v143
	global_store_dwordx2 v[4:5], v[14:15], off offset:-1024
	v_cvt_pk_bf16_f32 v16, v144, v145
	s_waitcnt lgkmcnt(0)
	v_add_f32_e32 v30, v30, v31
	ds_bpermute_b32 v31, v9, v30
	v_cvt_pk_bf16_f32 v17, v146, v147
	global_store_dwordx2 v[4:5], v[16:17], off offset:-512
	v_cvt_pk_bf16_f32 v18, v148, v149
	v_cvt_pk_bf16_f32 v19, v150, v151
	s_waitcnt lgkmcnt(0)
	v_add_f32_e32 v30, v30, v31
	ds_bpermute_b32 v31, v10, v30
	global_store_dwordx2 v[4:5], v[18:19], off
	v_cvt_pk_bf16_f32 v20, v152, v153
	v_cvt_pk_bf16_f32 v21, v154, v155
	global_store_dwordx2 v[4:5], v[20:21], off offset:512
	s_waitcnt lgkmcnt(0)
	v_add_f32_e32 v30, v30, v31
	ds_bpermute_b32 v31, v11, v30
	s_waitcnt lgkmcnt(0)
	v_add_f32_e32 v22, v30, v31
	ds_bpermute_b32 v23, v12, v22
	s_waitcnt lgkmcnt(0)
	v_add_f32_e32 v24, v22, v23
	ds_bpermute_b32 v25, v13, v24
	s_and_saveexec_b64 s[0:1], vcc
	s_cbranch_execz .Lprep_skip5
	s_waitcnt lgkmcnt(0)
	v_add_f32_e32 v24, v24, v25
	global_store_dword v[2:3], v24, off
; __device__ __forceinline__ int tid_opq() { int t = threadIdx.x; asm volatile("" : "+v"(t)); return t; }
; __device__ __forceinline__ int bid_opq() { int b = blockIdx.x; asm volatile("" : "+s"(b)); return b; }
; __device__ __forceinline__ unsigned cvtpk(float lo, float hi) { f32x2_t v = {lo, hi}; bf16x2_t b = __builtin_convertvector(v, bf16x2_t); return __builtin_bit_cast(unsigned, b); }
; __device__ __forceinline__ float wave_sum(float v) { v += __shfl_xor(v, 32); v += __shfl_xor(v, 16); v += __shfl_xor(v, 8); v += __shfl_xor(v, 4); v += __shfl_xor(v, 2); v += __shfl_xor(v, 1); return v; }
; __device__ void prep_rows(const float* __restrict__ X, bf16_t* __restrict__ XB, float* __restrict__ PS, int rows) {
;     ...
;     for (int r = gw; r < rows; r += stride) {
;         const f32x4* xr = (const f32x4*)(X + (size_t)r * DM); float ss = 0.f;
; #pragma unroll
;         for (int i = 0; i < 4; ++i) { const f32x4 v = xr[lane + 64 * i]; ss += v[0] * v[0] + v[1] * v[1] + v[2] * v[2] + v[3] * v[3];
;             u32x2 w; w.x = cvtpk(v[0], v[1]); w.y = cvtpk(v[2], v[3]); *(u32x2*)(XB + (size_t)r * DM + (lane + 64 * i) * 4) = w; }
;         ss = wave_sum(ss);
;         if (lane == 0) PS[r] = ss;
;     }
; __device__ __forceinline__ void run_phase(const Params& p, LAS unsigned char* lds, int ph, bool dummy) {
;     ...
;         for (int i = bid_opq() * 512 + tid_opq(); i < MTOK; i += gridDim.x * 512) RSB[i] = 0.f;
.Lprep_skip5:
	s_or_b64 exec, exec, s[0:1]
	v_lshl_add_u64 v[2:3], v[2:3], 0, s[50:51]
	v_lshl_add_u64 v[4:5], v[4:5], 0, s[52:53]
	v_mul_f32_e32 v30, v157, v157
	v_mul_f32_e32 v31, v161, v161
	v_mul_f32_e32 v32, v165, v165
	v_fmac_f32_e32 v30, v156, v156
	v_fmac_f32_e32 v31, v160, v160
	v_mul_f32_e32 v33, v169, v169
	v_fmac_f32_e32 v32, v164, v164
	v_fmac_f32_e32 v30, v158, v158
	v_fmac_f32_e32 v31, v162, v162
	v_fmac_f32_e32 v33, v168, v168
	v_fmac_f32_e32 v32, v166, v166
	v_fmac_f32_e32 v30, v159, v159
	v_fmac_f32_e32 v31, v163, v163
	v_fmac_f32_e32 v33, v170, v170
	v_fmac_f32_e32 v32, v167, v167
	v_add_f32_e32 v30, v30, v31
	v_add_f32_e32 v30, v30, v32
	v_fmac_f32_e32 v33, v171, v171
	v_add_f32_e32 v30, v30, v33
	ds_bpermute_b32 v31, v8, v30
	v_cvt_pk_bf16_f32 v14, v156, v157
	v_cvt_pk_bf16_f32 v15, v158, v159
	global_store_dwordx2 v[4:5], v[14:15], off offset:-1024
	v_cvt_pk_bf16_f32 v16, v160, v161
	s_waitcnt lgkmcnt(0)
	v_add_f32_e32 v30, v30, v31
	ds_bpermute_b32 v31, v9, v30
	v_cvt_pk_bf16_f32 v17, v162, v163
	global_store_dwordx2 v[4:5], v[16:17], off offset:-512
	v_cvt_pk_bf16_f32 v18, v164, v165
	v_cvt_pk_bf16_f32 v19, v166, v167
	s_waitcnt lgkmcnt(0)
	v_add_f32_e32 v30, v30, v31
	ds_bpermute_b32 v31, v10, v30
	global_store_dwordx2 v[4:5], v[18:19], off
	v_cvt_pk_bf16_f32 v20, v168, v169
	v_cvt_pk_bf16_f32 v21, v170, v171
	global_store_dwordx2 v[4:5], v[20:21], off offset:512
	s_waitcnt lgkmcnt(0)
	v_add_f32_e32 v30, v30, v31
	ds_bpermute_b32 v31, v11, v30
	s_waitcnt lgkmcnt(0)
	v_add_f32_e32 v22, v30, v31
	ds_bpermute_b32 v23, v12, v22
	s_waitcnt lgkmcnt(0)
	v_add_f32_e32 v24, v22, v23
	ds_bpermute_b32 v25, v13, v24
	s_and_saveexec_b64 s[0:1], vcc
	s_cbranch_execz .Lprep_skip6
	s_waitcnt lgkmcnt(0)
	v_add_f32_e32 v24, v24, v25
	global_store_dword v[2:3], v24, off
.Lprep_skip6:
	s_or_b64 exec, exec, s[0:1]
	v_lshl_add_u64 v[2:3], v[2:3], 0, s[50:51]
	v_lshl_add_u64 v[4:5], v[4:5], 0, s[52:53]
	v_mul_f32_e32 v30, v201, v201
	v_mul_f32_e32 v31, v205, v205
	v_mul_f32_e32 v32, v209, v209
	v_fmac_f32_e32 v30, v200, v200
	v_fmac_f32_e32 v31, v204, v204
	v_mul_f32_e32 v33, v213, v213
	v_fmac_f32_e32 v32, v208, v208
	v_fmac_f32_e32 v30, v202, v202
	v_fmac_f32_e32 v31, v206, v206
	v_fmac_f32_e32 v33, v212, v212
	v_fmac_f32_e32 v32, v210, v210
	v_fmac_f32_e32 v30, v203, v203
	v_fmac_f32_e32 v31, v207, v207
	v_fmac_f32_e32 v33, v214, v214
	v_fmac_f32_e32 v32, v211, v211
	v_add_f32_e32 v30, v30, v31
	v_add_f32_e32 v30, v30, v32
	v_fmac_f32_e32 v33, v215, v215
	v_add_f32_e32 v30, v30, v33
	ds_bpermute_b32 v31, v8, v30
	v_cvt_pk_bf16_f32 v14, v200, v201
	v_cvt_pk_bf16_f32 v15, v202, v203
	global_store_dwordx2 v[4:5], v[14:15], off offset:-1024
	v_cvt_pk_bf16_f32 v16, v204, v205
	s_waitcnt lgkmcnt(0)
	v_add_f32_e32 v30, v30, v31
	ds_bpermute_b32 v31, v9, v30
	v_cvt_pk_bf16_f32 v17, v206, v207
	global_store_dwordx2 v[4:5], v[16:17], off offset:-512
	v_cvt_pk_bf16_f32 v18, v208, v209
	v_cvt_pk_bf16_f32 v19, v210, v211
	s_waitcnt lgkmcnt(0)
	v_add_f32_e32 v30, v30, v31
	ds_bpermute_b32 v31, v10, v30
	global_store_dwordx2 v[4:5], v[18:19], off
	v_cvt_pk_bf16_f32 v20, v212, v213
	v_cvt_pk_bf16_f32 v21, v214, v215
	global_store_dwordx2 v[4:5], v[20:21], off offset:512
	s_waitcnt lgkmcnt(0)
	v_add_f32_e32 v30, v30, v31
	ds_bpermute_b32 v31, v11, v30
	s_waitcnt lgkmcnt(0)
	v_add_f32_e32 v22, v30, v31
	ds_bpermute_b32 v23, v12, v22
	s_waitcnt lgkmcnt(0)
	v_add_f32_e32 v24, v22, v23
	ds_bpermute_b32 v25, v13, v24
	s_and_saveexec_b64 s[0:1], vcc
	s_cbranch_execz .Lprep_skip7
	s_waitcnt lgkmcnt(0)
	v_add_f32_e32 v24, v24, v25
	global_store_dword v[2:3], v24, off
.Lprep_skip7:
	s_or_b64 exec, exec, s[0:1]
	s_waitcnt lgkmcnt(0)
.LBB0_663:
	s_or_b64 exec, exec, s[10:11]
	s_mov_b32 s0, s2
	v_mov_b32_e32 v0, v187
	s_nop 0
	v_lshl_add_u32 v2, s0, 9, v0
	s_movk_i32 s0, 0x4000
	v_cmp_gt_i32_e32 vcc, s0, v2
	s_and_saveexec_b64 s[0:1], vcc
	s_cbranch_execz .LBB0_19
	s_mov_b64 s[10:11], 0
